# attention stagger lengthened to 36 sleep units
# baseline (speedup 1.0000x reference)
; __global__ void __launch_bounds__(512, 2) fwd_mega(Args args) {
;     ...
;             const int hd = wave;
;             for (;;) {
;                 __syncthreads();
;                 if (tid == 0) *qslot = (int)atomicAdd(ctr + 16 + l * 8 + (bx & 7), 1u);
;                 __syncthreads();
;                 const int v = *qslot;
;                 if (v >= 68) break;
.LBB0_538:
	s_or_b64 exec, exec, s[2:3]
	v_mov_b32_e32 v0, s77
	s_waitcnt lgkmcnt(0)
	s_barrier
	ds_read_b32 v0, v0
	s_movk_i32 s2, 0x43
	s_waitcnt lgkmcnt(0)
	v_cmp_lt_i32_e32 vcc, s2, v0
	v_readfirstlane_b32 s4, v0
	s_mov_b64 s[2:3], -1
	s_cbranch_vccnz .LBB0_533
	v_and_b32_e32 v212, 63, v191
	v_readfirstlane_b32 s98, v191
	s_nop 3
	s_cmp_lt_u32 s98, 0x100
	s_cbranch_scc1 .Lattn_nostag
	s_sleep 36
